# MLA loop: packed-add row sums and 8-op max chains (fewer VALU per tile)
# speedup vs baseline: 1.0104x; 1.0020x over previous
.LBB0_562:
	s_mul_i32 s0, s22, 0xa000
	v_add_u32_e32 v204, s0, v178
	v_add_u32_e32 v205, s0, v180
	v_add_u32_e32 v189, s0, v181
	v_add_u32_e32 v188, s0, v182
	ds_read_b128 v[208:211], v204
	ds_read_b128 v[212:215], v205
	ds_read_b128 v[216:219], v189
	ds_read_b128 v[220:223], v188
	v_add_u32_e32 v199, s0, v184
	v_add_u32_e32 v200, s0, v185
	v_add_u32_e32 v201, s0, v186
	v_add_u32_e32 v207, s0, v187
	ds_read_b128 v[224:227], v204 offset:128
	ds_read_b128 v[228:231], v205 offset:128
	ds_read_b128 v[232:235], v189 offset:128
	ds_read_b128 v[236:239], v188 offset:128
	s_waitcnt lgkmcnt(7)
	v_mfma_f32_32x32x16_bf16 v[96:111], v[208:211], v[112:115], v[64:79]
	ds_read_b128 v[240:243], v204 offset:256
	s_waitcnt lgkmcnt(7)
	v_mfma_f32_32x32x16_bf16 v[96:111], v[212:215], v[116:119], v[96:111]
	ds_read_b128 v[248:251], v205 offset:256
	s_waitcnt lgkmcnt(7)
	v_mfma_f32_32x32x16_bf16 v[96:111], v[216:219], v[120:123], v[96:111]
	ds_read_b128 v[208:211], v189 offset:256
	s_waitcnt lgkmcnt(7)
	v_mfma_f32_32x32x16_bf16 v[96:111], v[220:223], v[124:127], v[96:111]
	ds_read_b128 v[212:215], v188 offset:256
	s_waitcnt lgkmcnt(7)
	v_mfma_f32_32x32x16_bf16 v[96:111], v[224:227], v[128:131], v[96:111]
	ds_read_b128 v[216:219], v199 offset:24576
	s_waitcnt lgkmcnt(7)
	v_mfma_f32_32x32x16_bf16 v[96:111], v[228:231], v[132:135], v[96:111]
	ds_read_b128 v[220:223], v199 offset:28672
	s_waitcnt lgkmcnt(7)
	v_mfma_f32_32x32x16_bf16 v[96:111], v[232:235], v[136:139], v[96:111]
	ds_read_b128 v[224:227], v199 offset:32768
	s_waitcnt lgkmcnt(7)
	v_mfma_f32_32x32x16_bf16 v[96:111], v[236:239], v[140:143], v[96:111]
	ds_read_b128 v[228:231], v199 offset:36864
	s_waitcnt lgkmcnt(7)
	v_mfma_f32_32x32x16_bf16 v[96:111], v[240:243], v[144:147], v[96:111]
	ds_read_b128 v[232:235], v200 offset:24576
	s_waitcnt lgkmcnt(7)
	v_mfma_f32_32x32x16_bf16 v[96:111], v[248:251], v[148:151], v[96:111]
	ds_read_b128 v[236:239], v200 offset:28672
	s_waitcnt lgkmcnt(7)
	v_mfma_f32_32x32x16_bf16 v[96:111], v[208:211], v[152:155], v[96:111]
	ds_read_b128 v[240:243], v200 offset:32768
	s_waitcnt lgkmcnt(7)
	v_mfma_f32_32x32x16_bf16 v[96:111], v[212:215], v[156:159], v[96:111]
	ds_read_b128 v[248:251], v200 offset:36864
	s_add_i32 s0, s22, 1
	s_cmp_lg_u32 s22, 2
	s_cselect_b32 s22, s0, 0
	s_add_i32 s0, s15, 1
	s_cmp_lg_u32 s15, 2
	s_cselect_b32 s15, s0, 0
	s_nop 4
	v_max3_f32 v80, v96, v97, v98
	v_max_f32_e32 v80, v80, v99
	v_max3_f32 v80, v80, v100, v101
	v_max3_f32 v80, v80, v102, v103
	v_max3_f32 v80, v80, v104, v105
	v_max3_f32 v80, v80, v106, v107
	v_max3_f32 v80, v80, v108, v109
	v_max3_f32 v206, v80, v110, v111
	v_cmp_ge_f32_e32 vcc, s85, v206
	s_cmp_eq_u64 vcc, exec
	s_cbranch_scc1 .Lmla_a_norescale
	ds_bpermute_b32 v64, v183, v206
	s_waitcnt lgkmcnt(0)
	v_max3_f32 v64, v206, v64, 0
	v_exp_f32_e64 v66, -v64
	v_add_f32_e32 v165, v165, v64
	v_xor_b32_e32 v80, 0x80000000, v165
	v_pk_add_f32 v[96:97], v[96:97], v[64:65] op_sel_hi:[1,0] neg_lo:[0,1] neg_hi:[0,1]
	v_mul_f32_e32 v164, v164, v66
	v_pk_mul_f32 v[14:15], v[14:15], v[66:67] op_sel_hi:[1,0]
	v_pk_mul_f32 v[12:13], v[12:13], v[66:67] op_sel_hi:[1,0]
	v_pk_mul_f32 v[10:11], v[10:11], v[66:67] op_sel_hi:[1,0]
	v_pk_mul_f32 v[8:9], v[8:9], v[66:67] op_sel_hi:[1,0]
	v_pk_mul_f32 v[6:7], v[6:7], v[66:67] op_sel_hi:[1,0]
	v_pk_mul_f32 v[4:5], v[4:5], v[66:67] op_sel_hi:[1,0]
	v_pk_mul_f32 v[2:3], v[2:3], v[66:67] op_sel_hi:[1,0]
	v_pk_mul_f32 v[0:1], v[0:1], v[66:67] op_sel_hi:[1,0]
	v_pk_mul_f32 v[30:31], v[30:31], v[66:67] op_sel_hi:[1,0]
	v_pk_mul_f32 v[28:29], v[28:29], v[66:67] op_sel_hi:[1,0]
	v_pk_mul_f32 v[26:27], v[26:27], v[66:67] op_sel_hi:[1,0]
	v_pk_mul_f32 v[24:25], v[24:25], v[66:67] op_sel_hi:[1,0]
	v_pk_mul_f32 v[22:23], v[22:23], v[66:67] op_sel_hi:[1,0]
	v_pk_mul_f32 v[20:21], v[20:21], v[66:67] op_sel_hi:[1,0]
	v_pk_mul_f32 v[18:19], v[18:19], v[66:67] op_sel_hi:[1,0]
	v_pk_mul_f32 v[16:17], v[16:17], v[66:67] op_sel_hi:[1,0]
	v_pk_mul_f32 v[46:47], v[46:47], v[66:67] op_sel_hi:[1,0]
	v_pk_mul_f32 v[44:45], v[44:45], v[66:67] op_sel_hi:[1,0]
	v_pk_mul_f32 v[42:43], v[42:43], v[66:67] op_sel_hi:[1,0]
	v_pk_mul_f32 v[40:41], v[40:41], v[66:67] op_sel_hi:[1,0]
	v_pk_mul_f32 v[38:39], v[38:39], v[66:67] op_sel_hi:[1,0]
	v_pk_mul_f32 v[36:37], v[36:37], v[66:67] op_sel_hi:[1,0]
	v_pk_mul_f32 v[34:35], v[34:35], v[66:67] op_sel_hi:[1,0]
	v_pk_mul_f32 v[32:33], v[32:33], v[66:67] op_sel_hi:[1,0]
	v_pk_mul_f32 v[62:63], v[62:63], v[66:67] op_sel_hi:[1,0]
	v_pk_mul_f32 v[60:61], v[60:61], v[66:67] op_sel_hi:[1,0]
	v_pk_mul_f32 v[58:59], v[58:59], v[66:67] op_sel_hi:[1,0]
	v_pk_mul_f32 v[56:57], v[56:57], v[66:67] op_sel_hi:[1,0]
	v_pk_mul_f32 v[54:55], v[54:55], v[66:67] op_sel_hi:[1,0]
	v_pk_mul_f32 v[52:53], v[52:53], v[66:67] op_sel_hi:[1,0]
	v_pk_mul_f32 v[50:51], v[50:51], v[66:67] op_sel_hi:[1,0]
	v_pk_mul_f32 v[48:49], v[48:49], v[66:67] op_sel_hi:[1,0]
	v_pk_add_f32 v[98:99], v[98:99], v[64:65] op_sel_hi:[1,0] neg_lo:[0,1] neg_hi:[0,1]
	v_pk_add_f32 v[100:101], v[100:101], v[64:65] op_sel_hi:[1,0] neg_lo:[0,1] neg_hi:[0,1]
	v_pk_add_f32 v[102:103], v[102:103], v[64:65] op_sel_hi:[1,0] neg_lo:[0,1] neg_hi:[0,1]
	v_pk_add_f32 v[104:105], v[104:105], v[64:65] op_sel_hi:[1,0] neg_lo:[0,1] neg_hi:[0,1]
	v_pk_add_f32 v[106:107], v[106:107], v[64:65] op_sel_hi:[1,0] neg_lo:[0,1] neg_hi:[0,1]
	v_pk_add_f32 v[108:109], v[108:109], v[64:65] op_sel_hi:[1,0] neg_lo:[0,1] neg_hi:[0,1]
	v_pk_add_f32 v[110:111], v[110:111], v[64:65] op_sel_hi:[1,0] neg_lo:[0,1] neg_hi:[0,1]
	v_mov_b32_e32 v64, v80
	v_mov_b32_e32 v65, v80
	v_mov_b32_e32 v66, v80
	v_mov_b32_e32 v67, v80
	v_mov_b32_e32 v68, v80
	v_mov_b32_e32 v69, v80
	v_mov_b32_e32 v70, v80
	v_mov_b32_e32 v71, v80
	v_mov_b32_e32 v72, v80
	v_mov_b32_e32 v73, v80
	v_mov_b32_e32 v74, v80
	v_mov_b32_e32 v75, v80
	v_mov_b32_e32 v76, v80
	v_mov_b32_e32 v77, v80
	v_mov_b32_e32 v78, v80
	v_mov_b32_e32 v79, v80
.Lmla_a_norescale:
	v_exp_f32_e32 v96, v96
	v_exp_f32_e32 v97, v97
	v_exp_f32_e32 v98, v98
	v_exp_f32_e32 v99, v99
	v_exp_f32_e32 v193, v100
	v_exp_f32_e32 v101, v101
	v_exp_f32_e32 v192, v102
	v_exp_f32_e32 v194, v103
	v_exp_f32_e32 v195, v104
	v_exp_f32_e32 v198, v105
	v_exp_f32_e32 v106, v106
	v_exp_f32_e32 v107, v107
	v_exp_f32_e32 v108, v108
	v_exp_f32_e32 v109, v109
	v_exp_f32_e32 v110, v110
	v_exp_f32_e32 v111, v111
	v_cvt_pk_bf16_f32 v102, v96, v97
	v_cvt_pk_bf16_f32 v103, v98, v99
	v_cvt_pk_bf16_f32 v104, v193, v101
	v_cvt_pk_bf16_f32 v105, v192, v194
	v_pk_add_f32 v[192:193], v[192:193], v[96:97]
	v_pk_add_f32 v[192:193], v[192:193], v[98:99]
	v_cvt_pk_bf16_f32 v96, v195, v198
	v_pk_add_f32 v[192:193], v[192:193], v[194:195]
	v_add_f32_e32 v101, v101, v198
	v_cvt_pk_bf16_f32 v97, v106, v107
	v_cvt_pk_bf16_f32 v98, v108, v109
	v_cvt_pk_bf16_f32 v99, v110, v111
	v_pk_add_f32 v[192:193], v[192:193], v[106:107]
	v_pk_add_f32 v[192:193], v[192:193], v[108:109]
	v_pk_add_f32 v[192:193], v[192:193], v[110:111]
	v_add_f32_e32 v100, v192, v193
	v_add_f32_e32 v100, v100, v101
	s_waitcnt lgkmcnt(7)
	v_mfma_f32_32x32x16_bf16 v[48:63], v[216:219], v[102:105], v[48:63]
	ds_read_b128 v[208:211], v204 offset:12288
	s_waitcnt lgkmcnt(7)
	v_mfma_f32_32x32x16_bf16 v[32:47], v[220:223], v[102:105], v[32:47]
	ds_read_b128 v[212:215], v205 offset:12288
	s_waitcnt lgkmcnt(7)
	v_mfma_f32_32x32x16_bf16 v[16:31], v[224:227], v[102:105], v[16:31]
	ds_read_b128 v[216:219], v189 offset:12288
	s_waitcnt lgkmcnt(7)
	v_mfma_f32_32x32x16_bf16 v[0:15], v[228:231], v[102:105], v[0:15]
	ds_read_b128 v[220:223], v188 offset:12288
	s_waitcnt lgkmcnt(7)
	v_mfma_f32_32x32x16_bf16 v[48:63], v[232:235], v[96:99], v[48:63]
	ds_read_b128 v[224:227], v204 offset:12416
	s_waitcnt lgkmcnt(7)
	v_mfma_f32_32x32x16_bf16 v[32:47], v[236:239], v[96:99], v[32:47]
	ds_read_b128 v[228:231], v205 offset:12416
	s_waitcnt lgkmcnt(7)
	v_mfma_f32_32x32x16_bf16 v[16:31], v[240:243], v[96:99], v[16:31]
	ds_read_b128 v[232:235], v189 offset:12416
	s_waitcnt lgkmcnt(7)
	v_mfma_f32_32x32x16_bf16 v[0:15], v[248:251], v[96:99], v[0:15]
	ds_read_b128 v[236:239], v188 offset:12416
	s_waitcnt lgkmcnt(7)
	v_mfma_f32_32x32x16_bf16 v[80:95], v[208:211], v[112:115], v[64:79]
	ds_read_b128 v[240:243], v204 offset:12544
	s_waitcnt lgkmcnt(7)
	v_mfma_f32_32x32x16_bf16 v[80:95], v[212:215], v[116:119], v[80:95]
	ds_read_b128 v[248:251], v205 offset:12544
	s_waitcnt lgkmcnt(7)
	v_mfma_f32_32x32x16_bf16 v[80:95], v[216:219], v[120:123], v[80:95]
	ds_read_b128 v[208:211], v189 offset:12544
	s_waitcnt lgkmcnt(7)
	v_mfma_f32_32x32x16_bf16 v[80:95], v[220:223], v[124:127], v[80:95]
	ds_read_b128 v[212:215], v188 offset:12544
	s_waitcnt lgkmcnt(7)
	v_mfma_f32_32x32x16_bf16 v[80:95], v[224:227], v[128:131], v[80:95]
	ds_read_b128 v[216:219], v201 offset:24576
	s_waitcnt lgkmcnt(7)
	v_mfma_f32_32x32x16_bf16 v[80:95], v[228:231], v[132:135], v[80:95]
	ds_read_b128 v[220:223], v201 offset:28672
	s_waitcnt lgkmcnt(7)
	v_mfma_f32_32x32x16_bf16 v[80:95], v[232:235], v[136:139], v[80:95]
	ds_read_b128 v[224:227], v201 offset:32768
	s_waitcnt lgkmcnt(7)
	v_mfma_f32_32x32x16_bf16 v[80:95], v[236:239], v[140:143], v[80:95]
	ds_read_b128 v[228:231], v201 offset:36864
	s_waitcnt lgkmcnt(7)
	v_mfma_f32_32x32x16_bf16 v[80:95], v[240:243], v[144:147], v[80:95]
	ds_read_b128 v[232:235], v207 offset:24576
	s_waitcnt lgkmcnt(7)
	v_mfma_f32_32x32x16_bf16 v[80:95], v[248:251], v[148:151], v[80:95]
	ds_read_b128 v[236:239], v207 offset:28672
	s_waitcnt lgkmcnt(7)
	v_mfma_f32_32x32x16_bf16 v[80:95], v[208:211], v[152:155], v[80:95]
	ds_read_b128 v[240:243], v207 offset:32768
	s_waitcnt lgkmcnt(7)
	v_mfma_f32_32x32x16_bf16 v[80:95], v[212:215], v[156:159], v[80:95]
	ds_read_b128 v[248:251], v207 offset:36864
	v_lshl_add_u64 v[166:167], v[166:167], 0, s[66:67]
	v_lshl_add_u64 v[168:169], v[168:169], 0, v[162:163]
	v_lshl_add_u64 v[170:171], v[170:171], 0, v[160:161]
	v_lshl_add_u64 v[172:173], v[172:173], 0, v[176:177]
	s_nop 7
	v_max3_f32 v96, v80, v81, v82
	v_max_f32_e32 v96, v96, v83
	v_max3_f32 v96, v96, v84, v85
	v_max3_f32 v96, v96, v86, v87
	v_max3_f32 v96, v96, v88, v89
	v_max3_f32 v96, v96, v90, v91
	v_max3_f32 v96, v96, v92, v93
	v_max3_f32 v97, v96, v94, v95
	v_cmp_ge_f32_e32 vcc, s85, v97
	v_add_f32_e32 v96, v164, v100
	s_cmp_eq_u64 vcc, exec
	s_cbranch_scc1 .Lmla_b_norescale
	ds_bpermute_b32 v64, v183, v97
	s_waitcnt lgkmcnt(0)
	v_max3_f32 v66, v97, v64, 0
	v_exp_f32_e64 v68, -v66
	v_add_f32_e32 v165, v165, v66
	v_xor_b32_e32 v64, 0x80000000, v165
	v_pk_add_f32 v[80:81], v[80:81], v[66:67] op_sel_hi:[1,0] neg_lo:[0,1] neg_hi:[0,1]
	v_pk_mul_f32 v[62:63], v[62:63], v[68:69] op_sel_hi:[1,0]
	v_pk_mul_f32 v[60:61], v[60:61], v[68:69] op_sel_hi:[1,0]
	v_pk_mul_f32 v[58:59], v[58:59], v[68:69] op_sel_hi:[1,0]
	v_pk_mul_f32 v[56:57], v[56:57], v[68:69] op_sel_hi:[1,0]
	v_pk_mul_f32 v[54:55], v[54:55], v[68:69] op_sel_hi:[1,0]
	v_pk_mul_f32 v[52:53], v[52:53], v[68:69] op_sel_hi:[1,0]
	v_pk_mul_f32 v[50:51], v[50:51], v[68:69] op_sel_hi:[1,0]
	v_pk_mul_f32 v[48:49], v[48:49], v[68:69] op_sel_hi:[1,0]
	v_pk_mul_f32 v[46:47], v[46:47], v[68:69] op_sel_hi:[1,0]
	v_pk_mul_f32 v[44:45], v[44:45], v[68:69] op_sel_hi:[1,0]
	v_pk_mul_f32 v[42:43], v[42:43], v[68:69] op_sel_hi:[1,0]
	v_pk_mul_f32 v[40:41], v[40:41], v[68:69] op_sel_hi:[1,0]
	v_pk_mul_f32 v[38:39], v[38:39], v[68:69] op_sel_hi:[1,0]
	v_pk_mul_f32 v[36:37], v[36:37], v[68:69] op_sel_hi:[1,0]
	v_pk_mul_f32 v[34:35], v[34:35], v[68:69] op_sel_hi:[1,0]
	v_pk_mul_f32 v[32:33], v[32:33], v[68:69] op_sel_hi:[1,0]
	v_pk_mul_f32 v[30:31], v[30:31], v[68:69] op_sel_hi:[1,0]
	v_pk_mul_f32 v[28:29], v[28:29], v[68:69] op_sel_hi:[1,0]
	v_pk_mul_f32 v[26:27], v[26:27], v[68:69] op_sel_hi:[1,0]
	v_pk_mul_f32 v[24:25], v[24:25], v[68:69] op_sel_hi:[1,0]
	v_pk_mul_f32 v[22:23], v[22:23], v[68:69] op_sel_hi:[1,0]
	v_pk_mul_f32 v[20:21], v[20:21], v[68:69] op_sel_hi:[1,0]
	v_pk_mul_f32 v[18:19], v[18:19], v[68:69] op_sel_hi:[1,0]
	v_pk_mul_f32 v[16:17], v[16:17], v[68:69] op_sel_hi:[1,0]
	v_pk_mul_f32 v[14:15], v[14:15], v[68:69] op_sel_hi:[1,0]
	v_pk_mul_f32 v[12:13], v[12:13], v[68:69] op_sel_hi:[1,0]
	v_pk_mul_f32 v[10:11], v[10:11], v[68:69] op_sel_hi:[1,0]
	v_pk_mul_f32 v[8:9], v[8:9], v[68:69] op_sel_hi:[1,0]
	v_pk_mul_f32 v[6:7], v[6:7], v[68:69] op_sel_hi:[1,0]
	v_pk_mul_f32 v[4:5], v[4:5], v[68:69] op_sel_hi:[1,0]
	v_pk_mul_f32 v[2:3], v[2:3], v[68:69] op_sel_hi:[1,0]
	v_pk_mul_f32 v[0:1], v[0:1], v[68:69] op_sel_hi:[1,0]
	v_pk_add_f32 v[82:83], v[82:83], v[66:67] op_sel_hi:[1,0] neg_lo:[0,1] neg_hi:[0,1]
	v_pk_add_f32 v[84:85], v[84:85], v[66:67] op_sel_hi:[1,0] neg_lo:[0,1] neg_hi:[0,1]
	v_pk_add_f32 v[86:87], v[86:87], v[66:67] op_sel_hi:[1,0] neg_lo:[0,1] neg_hi:[0,1]
	v_pk_add_f32 v[88:89], v[88:89], v[66:67] op_sel_hi:[1,0] neg_lo:[0,1] neg_hi:[0,1]
	v_pk_add_f32 v[90:91], v[90:91], v[66:67] op_sel_hi:[1,0] neg_lo:[0,1] neg_hi:[0,1]
	v_pk_add_f32 v[92:93], v[92:93], v[66:67] op_sel_hi:[1,0] neg_lo:[0,1] neg_hi:[0,1]
	v_pk_add_f32 v[94:95], v[94:95], v[66:67] op_sel_hi:[1,0] neg_lo:[0,1] neg_hi:[0,1]
	v_mul_f32_e32 v96, v96, v68
	v_mov_b32_e32 v65, v64
	v_mov_b32_e32 v66, v64
	v_mov_b32_e32 v67, v64
	v_mov_b32_e32 v68, v64
	v_mov_b32_e32 v69, v64
	v_mov_b32_e32 v70, v64
	v_mov_b32_e32 v71, v64
	v_mov_b32_e32 v72, v64
	v_mov_b32_e32 v73, v64
	v_mov_b32_e32 v74, v64
	v_mov_b32_e32 v75, v64
	v_mov_b32_e32 v76, v64
	v_mov_b32_e32 v77, v64
	v_mov_b32_e32 v78, v64
	v_mov_b32_e32 v79, v64
.Lmla_b_norescale:
	v_exp_f32_e32 v80, v80
	v_exp_f32_e32 v81, v81
	v_exp_f32_e32 v82, v82
	v_exp_f32_e32 v83, v83
	v_exp_f32_e32 v98, v84
	v_exp_f32_e32 v97, v85
	v_exp_f32_e32 v99, v86
	v_exp_f32_e32 v87, v87
	v_exp_f32_e32 v88, v88
	v_exp_f32_e32 v89, v89
	v_exp_f32_e32 v90, v90
	v_exp_f32_e32 v91, v91
	v_exp_f32_e32 v92, v92
	v_exp_f32_e32 v93, v93
	v_exp_f32_e32 v94, v94
	v_exp_f32_e32 v95, v95
	v_cvt_pk_bf16_f32 v84, v80, v81
	v_cvt_pk_bf16_f32 v85, v82, v83
	v_cvt_pk_bf16_f32 v86, v98, v97
	v_add_f32_e32 v100, v97, v87
	v_cvt_pk_bf16_f32 v87, v99, v87
	v_pk_add_f32 v[98:99], v[98:99], v[80:81]
	v_pk_add_f32 v[98:99], v[98:99], v[82:83]
	v_cvt_pk_bf16_f32 v80, v88, v89
	v_cvt_pk_bf16_f32 v81, v90, v91
	v_cvt_pk_bf16_f32 v82, v92, v93
	v_cvt_pk_bf16_f32 v83, v94, v95
	v_pk_add_f32 v[98:99], v[98:99], v[88:89]
	v_pk_add_f32 v[98:99], v[98:99], v[90:91]
	v_pk_add_f32 v[98:99], v[98:99], v[92:93]
	v_pk_add_f32 v[98:99], v[98:99], v[94:95]
	v_add_f32_e32 v100, v100, v98
	v_add_f32_e32 v100, v100, v99
	v_add_f32_e32 v164, v96, v100
	s_waitcnt lgkmcnt(7)
	v_mfma_f32_32x32x16_bf16 v[48:63], v[216:219], v[84:87], v[48:63]
	s_waitcnt lgkmcnt(6)
	v_mfma_f32_32x32x16_bf16 v[32:47], v[220:223], v[84:87], v[32:47]
	s_waitcnt lgkmcnt(5)
	v_mfma_f32_32x32x16_bf16 v[16:31], v[224:227], v[84:87], v[16:31]
	s_waitcnt lgkmcnt(4)
	v_mfma_f32_32x32x16_bf16 v[0:15], v[228:231], v[84:87], v[0:15]
	s_waitcnt lgkmcnt(3)
	v_mfma_f32_32x32x16_bf16 v[48:63], v[232:235], v[80:83], v[48:63]
	s_waitcnt lgkmcnt(2)
	v_mfma_f32_32x32x16_bf16 v[32:47], v[236:239], v[80:83], v[32:47]
	s_waitcnt lgkmcnt(1)
	v_mfma_f32_32x32x16_bf16 v[16:31], v[240:243], v[80:83], v[16:31]
	s_waitcnt lgkmcnt(0)
	v_mfma_f32_32x32x16_bf16 v[0:15], v[248:251], v[80:83], v[0:15]
	s_cmp_lg_u32 s14, s23
	s_cbranch_scc1 .LBB0_556
	ds_bpermute_b32 v64, v183, v164
	s_lshl_b32 s54, s21, 1
	v_lshlrev_b32_e32 v176, 3, v174
	s_waitcnt vmcnt(0) lgkmcnt(0)
	s_barrier
	v_add_f32_e32 v64, v164, v64
	v_div_scale_f32 v65, s[0:1], v64, v64, 1.0
	v_rcp_f32_e32 v66, v65
	v_div_scale_f32 v67, vcc, 1.0, v64, 1.0
	v_fma_f32 v68, -v65, v66, 1.0
	v_fmac_f32_e32 v66, v68, v66
	v_mul_f32_e32 v68, v67, v66
	v_fma_f32 v69, -v65, v68, v67
	v_fmac_f32_e32 v68, v69, v66
	v_fma_f32 v65, -v65, v68, v67
	v_div_fmas_f32 v65, v65, v66, v68
	v_mov_b64_e32 v[66:67], s[12:13]
	v_div_fixup_f32 v64, v65, v64, 1.0
	v_mad_i64_i32 v[66:67], s[0:1], v175, s78, v[66:67]
	v_lshl_add_u64 v[66:67], v[66:67], 0, s[54:55]
	v_pk_mul_f32 v[48:49], v[48:49], v[64:65] op_sel_hi:[1,0]
	v_pk_mul_f32 v[50:51], v[50:51], v[64:65] op_sel_hi:[1,0]
	v_pk_mul_f32 v[32:33], v[32:33], v[64:65] op_sel_hi:[1,0]
	v_pk_mul_f32 v[34:35], v[34:35], v[64:65] op_sel_hi:[1,0]
	v_pk_mul_f32 v[16:17], v[16:17], v[64:65] op_sel_hi:[1,0]
	v_pk_mul_f32 v[18:19], v[18:19], v[64:65] op_sel_hi:[1,0]
	v_pk_mul_f32 v[0:1], v[0:1], v[64:65] op_sel_hi:[1,0]
	v_pk_mul_f32 v[2:3], v[2:3], v[64:65] op_sel_hi:[1,0]
	v_lshl_add_u64 v[66:67], v[66:67], 0, v[176:177]
	v_cvt_pk_bf16_f32 v48, v48, v49
	v_cvt_pk_bf16_f32 v49, v50, v51
	v_cvt_pk_bf16_f32 v32, v32, v33
	v_cvt_pk_bf16_f32 v33, v34, v35
	v_cvt_pk_bf16_f32 v16, v16, v17
	v_cvt_pk_bf16_f32 v17, v18, v19
	v_cvt_pk_bf16_f32 v0, v0, v1
	v_cvt_pk_bf16_f32 v1, v2, v3
	global_store_dwordx2 v[66:67], v[48:49], off
	v_pk_mul_f32 v[48:49], v[52:53], v[64:65] op_sel_hi:[1,0]
	v_pk_mul_f32 v[50:51], v[54:55], v[64:65] op_sel_hi:[1,0]
	global_store_dwordx2 v[66:67], v[32:33], off offset:64
	v_pk_mul_f32 v[32:33], v[36:37], v[64:65] op_sel_hi:[1,0]
	v_pk_mul_f32 v[34:35], v[38:39], v[64:65] op_sel_hi:[1,0]
	global_store_dwordx2 v[66:67], v[16:17], off offset:128
	v_pk_mul_f32 v[16:17], v[20:21], v[64:65] op_sel_hi:[1,0]
	v_pk_mul_f32 v[18:19], v[22:23], v[64:65] op_sel_hi:[1,0]
	global_store_dwordx2 v[66:67], v[0:1], off offset:192
	v_pk_mul_f32 v[0:1], v[4:5], v[64:65] op_sel_hi:[1,0]
	v_pk_mul_f32 v[2:3], v[6:7], v[64:65] op_sel_hi:[1,0]
	v_cvt_pk_bf16_f32 v48, v48, v49
	v_cvt_pk_bf16_f32 v49, v50, v51
	v_cvt_pk_bf16_f32 v32, v32, v33
	v_cvt_pk_bf16_f32 v33, v34, v35
	v_cvt_pk_bf16_f32 v16, v16, v17
	v_cvt_pk_bf16_f32 v17, v18, v19
	v_cvt_pk_bf16_f32 v0, v0, v1
	v_cvt_pk_bf16_f32 v1, v2, v3
	global_store_dwordx2 v[66:67], v[48:49], off offset:16
	v_pk_mul_f32 v[48:49], v[56:57], v[64:65] op_sel_hi:[1,0]
	v_pk_mul_f32 v[50:51], v[58:59], v[64:65] op_sel_hi:[1,0]
	global_store_dwordx2 v[66:67], v[32:33], off offset:80
	v_pk_mul_f32 v[32:33], v[40:41], v[64:65] op_sel_hi:[1,0]
	v_pk_mul_f32 v[34:35], v[42:43], v[64:65] op_sel_hi:[1,0]
	global_store_dwordx2 v[66:67], v[16:17], off offset:144
	v_pk_mul_f32 v[16:17], v[24:25], v[64:65] op_sel_hi:[1,0]
	v_pk_mul_f32 v[18:19], v[26:27], v[64:65] op_sel_hi:[1,0]
	global_store_dwordx2 v[66:67], v[0:1], off offset:208
	v_pk_mul_f32 v[0:1], v[8:9], v[64:65] op_sel_hi:[1,0]
	v_pk_mul_f32 v[2:3], v[10:11], v[64:65] op_sel_hi:[1,0]
	v_cvt_pk_bf16_f32 v48, v48, v49
	v_cvt_pk_bf16_f32 v49, v50, v51
	v_cvt_pk_bf16_f32 v32, v32, v33
	v_cvt_pk_bf16_f32 v33, v34, v35
	v_cvt_pk_bf16_f32 v16, v16, v17
	v_cvt_pk_bf16_f32 v17, v18, v19
	v_cvt_pk_bf16_f32 v0, v0, v1
	v_cvt_pk_bf16_f32 v1, v2, v3
	global_store_dwordx2 v[66:67], v[48:49], off offset:32
	v_pk_mul_f32 v[48:49], v[60:61], v[64:65] op_sel_hi:[1,0]
	v_pk_mul_f32 v[50:51], v[62:63], v[64:65] op_sel_hi:[1,0]
	global_store_dwordx2 v[66:67], v[32:33], off offset:96
	v_pk_mul_f32 v[32:33], v[44:45], v[64:65] op_sel_hi:[1,0]
	v_pk_mul_f32 v[34:35], v[46:47], v[64:65] op_sel_hi:[1,0]
	global_store_dwordx2 v[66:67], v[16:17], off offset:160
	v_pk_mul_f32 v[16:17], v[28:29], v[64:65] op_sel_hi:[1,0]
	v_pk_mul_f32 v[18:19], v[30:31], v[64:65] op_sel_hi:[1,0]
	global_store_dwordx2 v[66:67], v[0:1], off offset:224
	v_pk_mul_f32 v[0:1], v[12:13], v[64:65] op_sel_hi:[1,0]
	v_pk_mul_f32 v[2:3], v[14:15], v[64:65] op_sel_hi:[1,0]
	s_add_i32 s20, s20, s36
	s_add_i32 s11, s11, s36
	v_cvt_pk_bf16_f32 v48, v48, v49
	v_cvt_pk_bf16_f32 v49, v50, v51
	v_cvt_pk_bf16_f32 v32, v32, v33
	v_cvt_pk_bf16_f32 v33, v34, v35
	v_cvt_pk_bf16_f32 v16, v16, v17
	v_cvt_pk_bf16_f32 v17, v18, v19
	v_cvt_pk_bf16_f32 v0, v0, v1
	v_cvt_pk_bf16_f32 v1, v2, v3
	s_cmp_ge_i32 s20, s10
	global_store_dwordx2 v[66:67], v[48:49], off offset:48
	global_store_dwordx2 v[66:67], v[32:33], off offset:112
	global_store_dwordx2 v[66:67], v[16:17], off offset:176
	global_store_dwordx2 v[66:67], v[0:1], off offset:240
	s_cbranch_scc0 .LBB0_541
